# compressed-branch pass 2: accumulator hand-over via the MFMA C operand instead of v_mov_b64 copies + s_nop 11
# baseline (speedup 1.0000x reference)
.LBB0_868:
	s_or_b64 exec, exec, s[10:11]
	v_cvt_pk_bf16_f32 v50, v50, v51
	v_cvt_pk_bf16_f32 v51, v52, v53
	v_cvt_pk_bf16_f32 v52, v54, v55
	v_cvt_pk_bf16_f32 v53, v56, v57
	v_cvt_pk_bf16_f32 v148, v58, v59
	v_cvt_pk_bf16_f32 v149, v60, v61
	v_cvt_pk_bf16_f32 v150, v62, v63
	v_cvt_pk_bf16_f32 v151, v64, v65
	ds_read_b128 v[54:57], v123 offset:9216
	ds_read_b128 v[58:61], v123 offset:9248
	ds_read_b128 v[62:65], v123 offset:9280
	ds_read_b128 v[152:155], v123 offset:9312
	s_add_i32 s10, s14, 1
	s_cmp_lg_u32 s10, 3
	s_cselect_b32 s22, s10, 0
	s_add_i32 s10, s22, 1
	s_cmp_lg_u32 s10, 3
	s_cselect_b32 s14, s10, 0
	v_cvt_pk_bf16_f32 v124, v66, v67
	v_cvt_pk_bf16_f32 v125, v68, v69
	v_cvt_pk_bf16_f32 v126, v70, v71
	v_cvt_pk_bf16_f32 v127, v72, v73
	v_cvt_pk_bf16_f32 v144, v74, v75
	v_cvt_pk_bf16_f32 v145, v76, v77
	v_cvt_pk_bf16_f32 v146, v78, v79
	v_cvt_pk_bf16_f32 v147, v80, v81
	s_waitcnt lgkmcnt(3)
	v_mfma_f32_32x32x16_bf16 v[18:33], v[54:57], v[124:127], v[18:33]
	s_waitcnt lgkmcnt(2)
	v_mfma_f32_32x32x16_bf16 v[18:33], v[58:61], v[144:147], v[18:33]
	s_waitcnt lgkmcnt(1)
	v_mfma_f32_32x32x16_bf16 v[18:33], v[62:65], v[50:53], v[18:33]
	s_waitcnt lgkmcnt(0)
	v_mfma_f32_32x32x16_bf16 v[66:81], v[152:155], v[148:151], v[18:33]
	s_nop 7
	ds_read_b128 v[18:21], v123 offset:13824
	ds_read_b128 v[22:25], v123 offset:13856
	ds_read_b128 v[26:29], v123 offset:13888
	ds_read_b128 v[30:33], v123 offset:13920
	s_waitcnt lgkmcnt(3)
	v_mfma_f32_32x32x16_bf16 v[2:17], v[18:21], v[124:127], v[2:17]
	s_waitcnt lgkmcnt(2)
	v_mfma_f32_32x32x16_bf16 v[2:17], v[22:25], v[144:147], v[2:17]
	s_waitcnt lgkmcnt(1)
	v_mfma_f32_32x32x16_bf16 v[2:17], v[26:29], v[50:53], v[2:17]
	s_waitcnt lgkmcnt(0)
	v_mfma_f32_32x32x16_bf16 v[50:65], v[30:33], v[148:151], v[2:17]
	s_add_i32 s21, s19, -2
	s_cmp_ge_i32 s21, s17
	s_cbranch_scc1 .LBB0_870
	s_mul_i32 s10, s14, 0x4900
	v_add_u32_e32 v2, s10, v101
	s_waitcnt vmcnt(1)
	ds_write_b128 v2, v[82:85]
	s_waitcnt vmcnt(0)
	ds_write_b128 v2, v[86:89] offset:9216
